# adds: NA local-window bias lookups batched (32 unconditional ds_read_b32 + v_cndmask instead of 32 serialized exec-masked round trips)
# speedup vs baseline: 1.0146x; 1.0061x over previous
; #define MFMA32(a, b, c) __builtin_amdgcn_mfma_f32_32x32x16_bf16((a), (b), (c), 0, 0, 0)
; #define ASCHED __builtin_amdgcn_sched_barrier(0)
; template <int DV, bool LOCAL>
; DI void attn_tile(const bf16x8 (&qf)[4], const lds_u8* Kb, const lds_u8* Vb, const int (&ko)[4], const int (&vo)[4], f32x16 (&o)[DV / 32], float& m, float& l, int hh,
;                   const float* rpbs, int drow, int cq, int c0) {
;     ...
;   f32x16 st[2];
;   {
;     bf16x8 kf[2][4];
; #pragma unroll
;     for (int t = 0; t < 2; ++t)
; #pragma unroll
;       for (int ks = 0; ks < 4; ++ks) kf[t][ks] = *(const lds_bf16x8*)(Kb + ko[ks] + t * 4096);
;     ASCHED;
; #pragma unroll
;     for (int t = 0; t < 2; ++t) {
;       f32x16 s;
; #pragma unroll
;       for (int i = 0; i < 16; ++i) s[i] = 0.f;
; #pragma unroll
;       for (int ks = 0; ks < 4; ++ks) s = MFMA32(kf[t][ks], qf[ks], s);
;       st[t] = s;
;     }
;   }
;   bf16x8 va[2][ND];
; #pragma unroll
;   for (int s2 = 0; s2 < 2; ++s2)
; #pragma unroll
;     for (int d = 0; d < ND; ++d) va[s2][d] = *(const lds_bf16x8*)(Vb + vo[s2] + d * 4096);
;   ASCHED;
;   float mx = -3.0e38f;
;   if (LOCAL) {
; #pragma unroll
;     for (int t = 0; t < 2; ++t)
; #pragma unroll
;       for (int i = 0; i < 16; ++i) {
;         const int ck = 32 * t + 16 * (i >> 3) + 8 * hh + (i & 7);
;         const int dc = ck - cq + 15;
;         const bool ok = (ck >= c0) && (ck < c0 + 16);
;         const int dcc = dc < 0 ? 0 : (dc > 30 ? 30 : dc);
;         const float z = ok ? __builtin_fmaf(st[t][i], QK_C, rpbs[drow * 31 + dcc]) : -1.0e30f;
;         st[t][i] = z; mx = fmaxf(mx, z);
.LBB0_506:
	s_add_i32 s41, s0, s54
	s_add_i32 s41, s41, -8
	s_cmp_ge_i32 s41, s72
	s_cselect_b64 s[52:53], -1, 0
	s_cmp_lt_i32 s41, s40
	s_cselect_b64 vcc, -1, 0
	s_and_b64 s[52:53], s[52:53], vcc
	v_mov_b64_e32 v[64:65], v[32:33]
	s_andn2_b64 vcc, exec, s[52:53]
	v_mov_b64_e32 v[62:63], v[30:31]
	v_mov_b64_e32 v[60:61], v[28:29]
	v_mov_b64_e32 v[58:59], v[26:27]
	v_mov_b64_e32 v[56:57], v[24:25]
	v_mov_b64_e32 v[54:55], v[22:23]
	v_mov_b64_e32 v[52:53], v[20:21]
	v_mov_b64_e32 v[50:51], v[18:19]
	v_mov_b64_e32 v[48:49], v[16:17]
	v_mov_b64_e32 v[46:47], v[14:15]
	v_mov_b64_e32 v[44:45], v[12:13]
	v_mov_b64_e32 v[42:43], v[10:11]
	v_mov_b64_e32 v[40:41], v[8:9]
	v_mov_b64_e32 v[38:39], v[6:7]
	v_mov_b64_e32 v[36:37], v[4:5]
	v_mov_b64_e32 v[34:35], v[2:3]
	v_mov_b32_e32 v148, v147
	v_mov_b32_e32 v200, v146
	s_cbranch_vccnz .LBB0_574
	v_add_u32_e32 v0, s55, v99
	v_add_u32_e32 v46, s55, v101
	v_add_u32_e32 v50, s55, v106
	v_add_u32_e32 v51, s55, v107
	ds_read_b128 v[34:37], v0
	ds_read_b128 v[38:41], v0 offset:4096
	ds_read_b128 v[42:45], v46
	ds_read_b128 v[82:85], v46 offset:4096
	ds_read_b128 v[46:49], v50
	ds_read_b128 v[86:89], v50 offset:4096
	ds_read_b128 v[90:93], v51
	ds_read_b128 v[94:97], v51 offset:4096
	s_waitcnt vmcnt(0) lgkmcnt(0)
	v_mfma_f32_32x32x16_bf16 v[50:65], v[34:37], v[74:77], 0
	v_add_u32_e32 v0, s55, v108
	v_mfma_f32_32x32x16_bf16 v[50:65], v[42:45], v[66:69], v[50:65]
	v_mfma_f32_32x32x16_bf16 v[50:65], v[46:49], v[70:73], v[50:65]
	v_mfma_f32_32x32x16_bf16 v[34:49], v[38:41], v[74:77], 0
	v_mfma_f32_32x32x16_bf16 v[34:49], v[82:85], v[66:69], v[34:49]
	v_mfma_f32_32x32x16_bf16 v[34:49], v[86:89], v[70:73], v[34:49]
	v_mfma_f32_32x32x16_bf16 v[50:65], v[90:93], v[78:81], v[50:65]
	v_mfma_f32_32x32x16_bf16 v[34:49], v[94:97], v[78:81], v[34:49]
	ds_read_b128 v[94:97], v0 offset:8192
	ds_read_b128 v[90:93], v0 offset:12288
	v_add_u32_e32 v0, s55, v109
	ds_read_b128 v[86:89], v0 offset:8192
	ds_read_b128 v[82:85], v0 offset:12288
	v_add_u32_e32 v148, s65, v145
	v_add_u32_e32 v0, s65, v144
	v_add_u32_e32 v150, s65, v143
	v_add_u32_e32 v149, s65, v141
	v_add_u32_e32 v152, s65, v140
	v_add_u32_e32 v151, s65, v139
	v_add_u32_e32 v154, s65, v138
	v_add_u32_e32 v153, s65, v137
	v_add_u32_e32 v156, s65, v136
	v_add_u32_e32 v155, s65, v135
	v_add_u32_e32 v191, s65, v134
	v_add_u32_e32 v157, s65, v133
	v_add_u32_e32 v193, s65, v132
	v_add_u32_e32 v192, s65, v131
	v_add_u32_e32 v195, s65, v129
	v_add_u32_e32 v194, s65, v128
	v_add_u32_e32 v197, s65, v127
	v_add_u32_e32 v196, s65, v126
	v_add_u32_e32 v199, s65, v125
	v_add_u32_e32 v198, s65, v124
	v_add_u32_e32 v202, s65, v123
	v_add_u32_e32 v201, s65, v122
	v_add_u32_e32 v204, s65, v121
	v_add_u32_e32 v203, s65, v120
	v_add_u32_e32 v206, s65, v119
	v_add_u32_e32 v205, s65, v118
	v_add_u32_e32 v208, s65, v117
	v_add_u32_e32 v207, s65, v116
	v_add_u32_e32 v210, s65, v115
	v_add_u32_e32 v209, s65, v114
	v_add_u32_e32 v212, s65, v113
	v_add_u32_e32 v211, s65, v112
	ds_read_b32 v148, v148
	ds_read_b32 v0, v0
	ds_read_b32 v150, v150
	ds_read_b32 v149, v149
	ds_read_b32 v152, v152
	ds_read_b32 v151, v151
	ds_read_b32 v154, v154
	ds_read_b32 v153, v153
	ds_read_b32 v156, v156
	ds_read_b32 v155, v155
	ds_read_b32 v191, v191
	ds_read_b32 v157, v157
	ds_read_b32 v193, v193
	ds_read_b32 v192, v192
	ds_read_b32 v195, v195
	ds_read_b32 v194, v194
	ds_read_b32 v197, v197
	ds_read_b32 v196, v196
	ds_read_b32 v199, v199
	ds_read_b32 v198, v198
	ds_read_b32 v202, v202
	ds_read_b32 v201, v201
	ds_read_b32 v204, v204
	ds_read_b32 v203, v203
	ds_read_b32 v206, v206
	ds_read_b32 v205, v205
	ds_read_b32 v208, v208
	ds_read_b32 v207, v207
	ds_read_b32 v210, v210
	ds_read_b32 v209, v209
	ds_read_b32 v212, v212
	ds_read_b32 v211, v211
	v_mov_b32_e32 v216, 0xf149f2ca
	s_waitcnt lgkmcnt(0)
; DI float xhalf_max(float v) { const auto r = __builtin_amdgcn_permlane32_swap(__float_as_uint(v), __float_as_uint(v), false, false); return fmaxf(__uint_as_float(r[0]), __uint_as_float(r[1])); }
; template <int DV, bool LOCAL>
; DI void attn_tile(const bf16x8 (&qf)[4], const lds_u8* Kb, const lds_u8* Vb, const int (&ko)[4], const int (&vo)[4], f32x16 (&o)[DV / 32], float& m, float& l, int hh,
;                   const float* rpbs, int drow, int cq, int c0) {
;     ...
;       for (int i = 0; i < 16; ++i) {
;         const int ck = 32 * t + 16 * (i >> 3) + 8 * hh + (i & 7);
;         const int dc = ck - cq + 15;
;         const bool ok = (ck >= c0) && (ck < c0 + 16);
;         const int dcc = dc < 0 ? 0 : (dc > 30 ? 30 : dc);
;         const float z = ok ? __builtin_fmaf(st[t][i], QK_C, rpbs[drow * 31 + dcc]) : -1.0e30f;
;         st[t][i] = z; mx = fmaxf(mx, z);
;       }
;   } else {
; #pragma unroll
;     for (int t = 0; t < 2; ++t)
; #pragma unroll
;       for (int i = 0; i < 16; ++i) mx = fmaxf(mx, st[t][i]);
;     mx *= QK_C;
;   }
;   mx = xhalf_max(mx);
;   if (!__all(mx <= m + 8.0f)) {
;     const float mn = fmaxf(m, mx);
;     const float alpha = __builtin_amdgcn_exp2f(m - mn);
;     m = mn; l *= alpha;
; #pragma unroll
;     for (int d = 0; d < ND; ++d) o[d] *= alpha;
;   }
	v_fmac_f32_e32 v148, 0x3e38aa3b, v50
	v_cndmask_b32_e64 v148, v216, v148, s[4:5]
	v_fmac_f32_e32 v0, 0x3e38aa3b, v51
	v_cndmask_b32_e64 v0, v216, v0, s[6:7]
	v_fmac_f32_e32 v150, 0x3e38aa3b, v52
	v_cndmask_b32_e64 v150, v216, v150, s[8:9]
	v_fmac_f32_e32 v149, 0x3e38aa3b, v53
	v_cndmask_b32_e64 v149, v216, v149, s[10:11]
	v_fmac_f32_e32 v152, 0x3e38aa3b, v54
	v_cndmask_b32_e64 v152, v216, v152, s[12:13]
	v_fmac_f32_e32 v151, 0x3e38aa3b, v55
	v_cndmask_b32_e64 v151, v216, v151, s[14:15]
	v_fmac_f32_e32 v154, 0x3e38aa3b, v56
	v_cndmask_b32_e64 v154, v216, v154, s[16:17]
	v_fmac_f32_e32 v153, 0x3e38aa3b, v57
	v_cndmask_b32_e64 v153, v216, v153, s[18:19]
	v_fmac_f32_e32 v156, 0x3e38aa3b, v58
	v_cndmask_b32_e64 v156, v216, v156, s[86:87]
	v_fmac_f32_e32 v155, 0x3e38aa3b, v59
	v_cndmask_b32_e64 v155, v216, v155, s[88:89]
	v_fmac_f32_e32 v191, 0x3e38aa3b, v60
	v_cndmask_b32_e64 v191, v216, v191, s[90:91]
	v_fmac_f32_e32 v157, 0x3e38aa3b, v61
	v_cndmask_b32_e64 v157, v216, v157, s[92:93]
	v_fmac_f32_e32 v193, 0x3e38aa3b, v62
	v_cndmask_b32_e64 v193, v216, v193, s[94:95]
	v_fmac_f32_e32 v192, 0x3e38aa3b, v63
	v_cndmask_b32_e64 v192, v216, v192, s[96:97]
	v_fmac_f32_e32 v195, 0x3e38aa3b, v64
	v_cndmask_b32_e64 v195, v216, v195, s[68:69]
	v_fmac_f32_e32 v194, 0x3e38aa3b, v65
	v_cndmask_b32_e64 v194, v216, v194, s[48:49]
	v_fmac_f32_e32 v197, 0x3e38aa3b, v34
	v_cndmask_b32_e64 v197, v216, v197, s[76:77]
	v_fmac_f32_e32 v196, 0x3e38aa3b, v35
	v_cndmask_b32_e64 v196, v216, v196, s[78:79]
	v_fmac_f32_e32 v199, 0x3e38aa3b, v36
	v_cndmask_b32_e64 v199, v216, v199, s[74:75]
	v_fmac_f32_e32 v198, 0x3e38aa3b, v37
	v_cndmask_b32_e64 v198, v216, v198, s[38:39]
	v_fmac_f32_e32 v202, 0x3e38aa3b, v38
	v_cndmask_b32_e64 v202, v216, v202, s[56:57]
	v_fmac_f32_e32 v201, 0x3e38aa3b, v39
	v_cndmask_b32_e64 v201, v216, v201, s[58:59]
	v_fmac_f32_e32 v204, 0x3e38aa3b, v40
	v_cndmask_b32_e64 v204, v216, v204, s[60:61]
	v_fmac_f32_e32 v203, 0x3e38aa3b, v41
	v_cndmask_b32_e64 v203, v216, v203, s[66:67]
	v_fmac_f32_e32 v206, 0x3e38aa3b, v42
	v_cndmask_b32_e64 v206, v216, v206, s[20:21]
	v_fmac_f32_e32 v205, 0x3e38aa3b, v43
	v_cndmask_b32_e64 v205, v216, v205, s[22:23]
	v_fmac_f32_e32 v208, 0x3e38aa3b, v44
	v_cndmask_b32_e64 v208, v216, v208, s[24:25]
	v_fmac_f32_e32 v207, 0x3e38aa3b, v45
	v_cndmask_b32_e64 v207, v216, v207, s[26:27]
	v_fmac_f32_e32 v210, 0x3e38aa3b, v46
	v_cndmask_b32_e64 v210, v216, v210, s[28:29]
	v_fmac_f32_e32 v209, 0x3e38aa3b, v47
	v_cndmask_b32_e64 v209, v216, v209, s[30:31]
	v_fmac_f32_e32 v212, 0x3e38aa3b, v48
	v_cndmask_b32_e64 v212, v216, v212, s[34:35]
	v_fmac_f32_e32 v211, 0x3e38aa3b, v49
	v_cndmask_b32_e64 v211, v216, v211, s[36:37]
	s_mov_b32 s41, 0xff61b1e6
	v_max3_f32 v34, v148, s41, v0
	v_max3_f32 v34, v34, v150, v149
	v_max3_f32 v34, v34, v152, v151
	v_max3_f32 v34, v34, v154, v153
	v_max3_f32 v34, v34, v156, v155
	v_max3_f32 v34, v34, v191, v157
	v_max3_f32 v34, v34, v193, v192
	v_max3_f32 v34, v34, v195, v194
	v_max3_f32 v34, v34, v197, v196
	v_max3_f32 v34, v34, v199, v198
	v_max3_f32 v34, v34, v202, v201
	v_max3_f32 v34, v34, v204, v203
	v_max3_f32 v34, v34, v206, v205
	v_max3_f32 v34, v34, v208, v207
	v_max3_f32 v34, v34, v210, v209
	v_max3_f32 v34, v34, v212, v211
	v_mov_b32_e32 v35, v34
	s_nop 1
	v_permlane32_swap_b32_e32 v34, v35
	v_max_f32_e32 v35, v35, v35
	v_max_f32_e32 v34, v34, v34
	v_max_f32_e32 v214, v34, v35
	v_add_f32_e32 v34, 0x41000000, v146
	v_cmp_le_f32_e32 vcc, v214, v34
	v_mov_b64_e32 v[64:65], v[32:33]
	s_cmp_eq_u64 vcc, exec
	v_mov_b32_e32 v200, v146
	v_mov_b32_e32 v213, v147
	v_mov_b64_e32 v[62:63], v[30:31]
	v_mov_b64_e32 v[60:61], v[28:29]
	v_mov_b64_e32 v[58:59], v[26:27]
	v_mov_b64_e32 v[56:57], v[24:25]
	v_mov_b64_e32 v[54:55], v[22:23]
	v_mov_b64_e32 v[52:53], v[20:21]
	v_mov_b64_e32 v[50:51], v[18:19]
	v_mov_b64_e32 v[48:49], v[16:17]
	v_mov_b64_e32 v[46:47], v[14:15]
	v_mov_b64_e32 v[44:45], v[12:13]
	v_mov_b64_e32 v[42:43], v[10:11]
	v_mov_b64_e32 v[40:41], v[8:9]
	v_mov_b64_e32 v[38:39], v[6:7]
	v_mov_b64_e32 v[36:37], v[4:5]
	v_mov_b64_e32 v[34:35], v[2:3]
	s_cbranch_scc1 .LBB0_573
	v_max_f32_e32 v34, v214, v214
	v_max_f32_e32 v35, v146, v146
	v_max_f32_e32 v200, v35, v34
	v_sub_f32_e32 v34, v146, v200
	v_exp_f32_e32 v34, v34
	s_nop 0
	v_mul_f32_e32 v213, v147, v34
	v_pk_mul_f32 v[64:65], v[32:33], v[34:35] op_sel_hi:[1,0]
	v_pk_mul_f32 v[62:63], v[30:31], v[34:35] op_sel_hi:[1,0]
	v_pk_mul_f32 v[60:61], v[28:29], v[34:35] op_sel_hi:[1,0]
	v_pk_mul_f32 v[58:59], v[26:27], v[34:35] op_sel_hi:[1,0]
	v_pk_mul_f32 v[56:57], v[24:25], v[34:35] op_sel_hi:[1,0]
	v_pk_mul_f32 v[54:55], v[22:23], v[34:35] op_sel_hi:[1,0]
	v_pk_mul_f32 v[52:53], v[20:21], v[34:35] op_sel_hi:[1,0]
	v_pk_mul_f32 v[50:51], v[18:19], v[34:35] op_sel_hi:[1,0]
	v_pk_mul_f32 v[48:49], v[16:17], v[34:35] op_sel_hi:[1,0]
	v_pk_mul_f32 v[46:47], v[14:15], v[34:35] op_sel_hi:[1,0]
	v_pk_mul_f32 v[44:45], v[12:13], v[34:35] op_sel_hi:[1,0]
	v_pk_mul_f32 v[42:43], v[10:11], v[34:35] op_sel_hi:[1,0]
	v_pk_mul_f32 v[40:41], v[8:9], v[34:35] op_sel_hi:[1,0]
	v_pk_mul_f32 v[38:39], v[6:7], v[34:35] op_sel_hi:[1,0]
	v_pk_mul_f32 v[36:37], v[4:5], v[34:35] op_sel_hi:[1,0]
	v_pk_mul_f32 v[34:35], v[2:3], v[34:35] op_sel_hi:[1,0]
